# GLU-tile in-proj epilogue also rewritten with packed f32; both cheap epilogues now generated
# speedup vs baseline: 1.0016x; 1.0016x over previous
; __device__ __forceinline__ unsigned cvt_pk_bf16(float lo, float hi) { unsigned r; asm volatile("v_cvt_pk_bf16_f32 %0, %1, %2" : "=v"(r) : "v"(lo), "v"(hi)); return r; }
; __device__ __forceinline__ float sigmoidf_(float v) { return __builtin_amdgcn_rcpf(1.f + __expf(-v)); }
;     __device__ __forceinline__ void operator()(const f32x4 (&acc)[2][2][4][2], const pg8::Unit& u, int wr, int wc, int fr, int fq) const {
;     ...
;             bf16_t* G = (bf16_t*)(ws + WS_G);
;             const int chb = 128 * (pn - 10) + 16 * wc + 4 * fq;
;             const int odd = fq & 1;
; #pragma unroll
;             for (int ai = 0; ai < 2; ++ai)
; #pragma unroll
;                 for (int mp = 0; mp < 2; ++mp) {
;                     const size_t row = (size_t)(row0 + ai * 128 + (2 * mp + odd) * 16);
; #pragma unroll
;                     for (int bj = 0; bj < 2; ++bj) {
;                         const f32x4 ua = acc[ai][bj][2 * mp][0], ga = acc[ai][bj][2 * mp][1], ub = acc[ai][bj][2 * mp + 1][0], gb = acc[ai][bj][2 * mp + 1][1];
;                         const unsigned a0 = cvt_pk_bf16(ua[0] * sigmoidf_(ga[0]), ua[1] * sigmoidf_(ga[1])), a1 = cvt_pk_bf16(ua[2] * sigmoidf_(ga[2]), ua[3] * sigmoidf_(ga[3]));
;                         const unsigned b0 = cvt_pk_bf16(ub[0] * sigmoidf_(gb[0]), ub[1] * sigmoidf_(gb[1])), b1 = cvt_pk_bf16(ub[2] * sigmoidf_(gb[2]), ub[3] * sigmoidf_(gb[3]));
;                         asm volatile("s_nop 1" ::: "memory");
;                         const u32x2 s0 = __builtin_amdgcn_permlane16_swap(a0, b0, false, false), s1 = __builtin_amdgcn_permlane16_swap(a1, b1, false, false);
;                         *(u32x4*)(G + row * 512 + (chb - 4 * odd) + 64 * bj) = (u32x4){s0[0], s1[0], s0[1], s1[1]};
;                     }
.LBB0_188:
	s_add_i32 s4, s10, -10
	s_cmp_gt_u32 s4, 3
	s_cbranch_scc1 .Lgate_new
	s_add_u32 s14, s70, 0x11b00000
	s_addc_u32 s15, s71, 0
	v_lshl_add_u32 v173, s10, 7, v184
	v_lshlrev_b32_e32 v173, 1, v173
	v_or_b32_e32 v132, v172, v178
	v_lshl_add_u32 v173, v132, 10, v173
	v_mov_b32_e32 v130, 0xbfb8aa3b
	v_mov_b32_e32 v131, 0xbfb8aa3b
	s_add_u32 s4, s14, 0
	s_addc_u32 s5, s15, 0
	v_pk_mul_f32 v[132:133], v[126:127], v[130:131]
	v_pk_mul_f32 v[134:135], v[128:129], v[130:131]
	v_pk_mul_f32 v[136:137], v[118:119], v[130:131]
	v_pk_mul_f32 v[138:139], v[120:121], v[130:131]
	v_exp_f32_e32 v132, v132
	v_exp_f32_e32 v133, v133
	v_exp_f32_e32 v134, v134
	v_exp_f32_e32 v135, v135
	v_exp_f32_e32 v136, v136
	v_exp_f32_e32 v137, v137
	v_exp_f32_e32 v138, v138
	v_exp_f32_e32 v139, v139
	v_pk_add_f32 v[132:133], v[132:133], 1.0 op_sel_hi:[1,0]
	v_pk_add_f32 v[134:135], v[134:135], 1.0 op_sel_hi:[1,0]
	v_pk_add_f32 v[136:137], v[136:137], 1.0 op_sel_hi:[1,0]
	v_pk_add_f32 v[138:139], v[138:139], 1.0 op_sel_hi:[1,0]
	v_rcp_f32_e32 v132, v132
	v_rcp_f32_e32 v133, v133
	v_rcp_f32_e32 v134, v134
	v_rcp_f32_e32 v135, v135
	v_rcp_f32_e32 v136, v136
	v_rcp_f32_e32 v137, v137
	v_rcp_f32_e32 v138, v138
	v_rcp_f32_e32 v139, v139
	v_pk_mul_f32 v[132:133], v[94:95], v[132:133]
	v_pk_mul_f32 v[134:135], v[96:97], v[134:135]
	v_pk_mul_f32 v[136:137], v[90:91], v[136:137]
	v_pk_mul_f32 v[138:139], v[92:93], v[138:139]
	v_cvt_pk_bf16_f32 v140, v132, v133
	v_cvt_pk_bf16_f32 v141, v134, v135
	v_cvt_pk_bf16_f32 v142, v136, v137
	v_cvt_pk_bf16_f32 v143, v138, v139
	s_nop 1
	v_permlane16_swap_b32_e32 v140, v142
	v_permlane16_swap_b32_e32 v141, v143
	s_nop 1
	global_store_dwordx4 v173, v[140:143], s[4:5] offset:0
	v_pk_mul_f32 v[132:133], v[78:79], v[130:131]
	v_pk_mul_f32 v[134:135], v[80:81], v[130:131]
	v_pk_mul_f32 v[136:137], v[74:75], v[130:131]
	v_pk_mul_f32 v[138:139], v[76:77], v[130:131]
	v_exp_f32_e32 v132, v132
	v_exp_f32_e32 v133, v133
	v_exp_f32_e32 v134, v134
	v_exp_f32_e32 v135, v135
	v_exp_f32_e32 v136, v136
	v_exp_f32_e32 v137, v137
	v_exp_f32_e32 v138, v138
	v_exp_f32_e32 v139, v139
	v_pk_add_f32 v[132:133], v[132:133], 1.0 op_sel_hi:[1,0]
	v_pk_add_f32 v[134:135], v[134:135], 1.0 op_sel_hi:[1,0]
	v_pk_add_f32 v[136:137], v[136:137], 1.0 op_sel_hi:[1,0]
	v_pk_add_f32 v[138:139], v[138:139], 1.0 op_sel_hi:[1,0]
	v_rcp_f32_e32 v132, v132
	v_rcp_f32_e32 v133, v133
	v_rcp_f32_e32 v134, v134
	v_rcp_f32_e32 v135, v135
	v_rcp_f32_e32 v136, v136
	v_rcp_f32_e32 v137, v137
	v_rcp_f32_e32 v138, v138
	v_rcp_f32_e32 v139, v139
	v_pk_mul_f32 v[132:133], v[122:123], v[132:133]
	v_pk_mul_f32 v[134:135], v[124:125], v[134:135]
	v_pk_mul_f32 v[136:137], v[114:115], v[136:137]
	v_pk_mul_f32 v[138:139], v[116:117], v[138:139]
	v_cvt_pk_bf16_f32 v144, v132, v133
	v_cvt_pk_bf16_f32 v145, v134, v135
	v_cvt_pk_bf16_f32 v146, v136, v137
	v_cvt_pk_bf16_f32 v147, v138, v139
	s_nop 1
	v_permlane16_swap_b32_e32 v144, v146
	v_permlane16_swap_b32_e32 v145, v147
	s_nop 1
	global_store_dwordx4 v173, v[144:147], s[4:5] offset:128
	s_add_u32 s4, s14, 32768
	s_addc_u32 s5, s15, 0
	v_pk_mul_f32 v[132:133], v[110:111], v[130:131]
	v_pk_mul_f32 v[134:135], v[112:113], v[130:131]
	v_pk_mul_f32 v[136:137], v[102:103], v[130:131]
	v_pk_mul_f32 v[138:139], v[104:105], v[130:131]
	v_exp_f32_e32 v132, v132
	v_exp_f32_e32 v133, v133
	v_exp_f32_e32 v134, v134
	v_exp_f32_e32 v135, v135
	v_exp_f32_e32 v136, v136
	v_exp_f32_e32 v137, v137
	v_exp_f32_e32 v138, v138
	v_exp_f32_e32 v139, v139
	v_pk_add_f32 v[132:133], v[132:133], 1.0 op_sel_hi:[1,0]
	v_pk_add_f32 v[134:135], v[134:135], 1.0 op_sel_hi:[1,0]
	v_pk_add_f32 v[136:137], v[136:137], 1.0 op_sel_hi:[1,0]
	v_pk_add_f32 v[138:139], v[138:139], 1.0 op_sel_hi:[1,0]
	v_rcp_f32_e32 v132, v132
	v_rcp_f32_e32 v133, v133
	v_rcp_f32_e32 v134, v134
	v_rcp_f32_e32 v135, v135
	v_rcp_f32_e32 v136, v136
	v_rcp_f32_e32 v137, v137
	v_rcp_f32_e32 v138, v138
	v_rcp_f32_e32 v139, v139
	v_pk_mul_f32 v[132:133], v[86:87], v[132:133]
	v_pk_mul_f32 v[134:135], v[88:89], v[134:135]
	v_pk_mul_f32 v[136:137], v[82:83], v[136:137]
	v_pk_mul_f32 v[138:139], v[84:85], v[138:139]
	v_cvt_pk_bf16_f32 v140, v132, v133
	v_cvt_pk_bf16_f32 v141, v134, v135
	v_cvt_pk_bf16_f32 v142, v136, v137
	v_cvt_pk_bf16_f32 v143, v138, v139
	s_nop 1
	v_permlane16_swap_b32_e32 v140, v142
	v_permlane16_swap_b32_e32 v141, v143
	s_nop 1
	global_store_dwordx4 v173, v[140:143], s[4:5] offset:0
	v_pk_mul_f32 v[132:133], v[70:71], v[130:131]
	v_pk_mul_f32 v[134:135], v[72:73], v[130:131]
	v_pk_mul_f32 v[136:137], v[66:67], v[130:131]
	v_pk_mul_f32 v[138:139], v[68:69], v[130:131]
	v_exp_f32_e32 v132, v132
	v_exp_f32_e32 v133, v133
	v_exp_f32_e32 v134, v134
	v_exp_f32_e32 v135, v135
	v_exp_f32_e32 v136, v136
	v_exp_f32_e32 v137, v137
	v_exp_f32_e32 v138, v138
	v_exp_f32_e32 v139, v139
	v_pk_add_f32 v[132:133], v[132:133], 1.0 op_sel_hi:[1,0]
	v_pk_add_f32 v[134:135], v[134:135], 1.0 op_sel_hi:[1,0]
	v_pk_add_f32 v[136:137], v[136:137], 1.0 op_sel_hi:[1,0]
	v_pk_add_f32 v[138:139], v[138:139], 1.0 op_sel_hi:[1,0]
	v_rcp_f32_e32 v132, v132
	v_rcp_f32_e32 v133, v133
	v_rcp_f32_e32 v134, v134
	v_rcp_f32_e32 v135, v135
	v_rcp_f32_e32 v136, v136
	v_rcp_f32_e32 v137, v137
	v_rcp_f32_e32 v138, v138
	v_rcp_f32_e32 v139, v139
	v_pk_mul_f32 v[132:133], v[106:107], v[132:133]
	v_pk_mul_f32 v[134:135], v[108:109], v[134:135]
	v_pk_mul_f32 v[136:137], v[98:99], v[136:137]
	v_pk_mul_f32 v[138:139], v[100:101], v[138:139]
	v_cvt_pk_bf16_f32 v144, v132, v133
	v_cvt_pk_bf16_f32 v145, v134, v135
	v_cvt_pk_bf16_f32 v146, v136, v137
; __device__ __forceinline__ unsigned cvt_pk_bf16(float lo, float hi) { unsigned r; asm volatile("v_cvt_pk_bf16_f32 %0, %1, %2" : "=v"(r) : "v"(lo), "v"(hi)); return r; }
; __device__ __forceinline__ float sigmoidf_(float v) { return __builtin_amdgcn_rcpf(1.f + __expf(-v)); }
;     __device__ __forceinline__ void operator()(const f32x4 (&acc)[2][2][4][2], const pg8::Unit& u, int wr, int wc, int fr, int fq) const {
;     ...
;             for (int ai = 0; ai < 2; ++ai)
; #pragma unroll
;                 for (int mp = 0; mp < 2; ++mp) {
;                     const size_t row = (size_t)(row0 + ai * 128 + (2 * mp + odd) * 16);
; #pragma unroll
;                     for (int bj = 0; bj < 2; ++bj) {
;                         const f32x4 ua = acc[ai][bj][2 * mp][0], ga = acc[ai][bj][2 * mp][1], ub = acc[ai][bj][2 * mp + 1][0], gb = acc[ai][bj][2 * mp + 1][1];
;                         const unsigned a0 = cvt_pk_bf16(ua[0] * sigmoidf_(ga[0]), ua[1] * sigmoidf_(ga[1])), a1 = cvt_pk_bf16(ua[2] * sigmoidf_(ga[2]), ua[3] * sigmoidf_(ga[3]));
;                         const unsigned b0 = cvt_pk_bf16(ub[0] * sigmoidf_(gb[0]), ub[1] * sigmoidf_(gb[1])), b1 = cvt_pk_bf16(ub[2] * sigmoidf_(gb[2]), ub[3] * sigmoidf_(gb[3]));
;                         asm volatile("s_nop 1" ::: "memory");
;                         const u32x2 s0 = __builtin_amdgcn_permlane16_swap(a0, b0, false, false), s1 = __builtin_amdgcn_permlane16_swap(a1, b1, false, false);
;                         *(u32x4*)(G + row * 512 + (chb - 4 * odd) + 64 * bj) = (u32x4){s0[0], s1[0], s0[1], s1[1]};
;                     }
	v_cvt_pk_bf16_f32 v147, v138, v139
	s_nop 1
	v_permlane16_swap_b32_e32 v144, v146
	v_permlane16_swap_b32_e32 v145, v147
	s_nop 1
	global_store_dwordx4 v173, v[144:147], s[4:5] offset:128
	s_add_u32 s4, s14, 131072
	s_addc_u32 s5, s15, 0
	v_pk_mul_f32 v[132:133], v[62:63], v[130:131]
	v_pk_mul_f32 v[134:135], v[64:65], v[130:131]
	v_pk_mul_f32 v[136:137], v[54:55], v[130:131]
	v_pk_mul_f32 v[138:139], v[56:57], v[130:131]
	v_exp_f32_e32 v132, v132
	v_exp_f32_e32 v133, v133
	v_exp_f32_e32 v134, v134
	v_exp_f32_e32 v135, v135
	v_exp_f32_e32 v136, v136
	v_exp_f32_e32 v137, v137
	v_exp_f32_e32 v138, v138
	v_exp_f32_e32 v139, v139
	v_pk_add_f32 v[132:133], v[132:133], 1.0 op_sel_hi:[1,0]
	v_pk_add_f32 v[134:135], v[134:135], 1.0 op_sel_hi:[1,0]
	v_pk_add_f32 v[136:137], v[136:137], 1.0 op_sel_hi:[1,0]
	v_pk_add_f32 v[138:139], v[138:139], 1.0 op_sel_hi:[1,0]
	v_rcp_f32_e32 v132, v132
	v_rcp_f32_e32 v133, v133
	v_rcp_f32_e32 v134, v134
	v_rcp_f32_e32 v135, v135
	v_rcp_f32_e32 v136, v136
	v_rcp_f32_e32 v137, v137
	v_rcp_f32_e32 v138, v138
	v_rcp_f32_e32 v139, v139
	v_pk_mul_f32 v[132:133], v[30:31], v[132:133]
	v_pk_mul_f32 v[134:135], v[32:33], v[134:135]
	v_pk_mul_f32 v[136:137], v[26:27], v[136:137]
	v_pk_mul_f32 v[138:139], v[28:29], v[138:139]
	v_cvt_pk_bf16_f32 v140, v132, v133
	v_cvt_pk_bf16_f32 v141, v134, v135
	v_cvt_pk_bf16_f32 v142, v136, v137
	v_cvt_pk_bf16_f32 v143, v138, v139
	s_nop 1
	v_permlane16_swap_b32_e32 v140, v142
	v_permlane16_swap_b32_e32 v141, v143
	s_nop 1
	global_store_dwordx4 v173, v[140:143], s[4:5] offset:0
	v_pk_mul_f32 v[132:133], v[14:15], v[130:131]
	v_pk_mul_f32 v[134:135], v[16:17], v[130:131]
	v_pk_mul_f32 v[136:137], v[10:11], v[130:131]
	v_pk_mul_f32 v[138:139], v[12:13], v[130:131]
	v_exp_f32_e32 v132, v132
	v_exp_f32_e32 v133, v133
	v_exp_f32_e32 v134, v134
	v_exp_f32_e32 v135, v135
	v_exp_f32_e32 v136, v136
	v_exp_f32_e32 v137, v137
	v_exp_f32_e32 v138, v138
	v_exp_f32_e32 v139, v139
	v_pk_add_f32 v[132:133], v[132:133], 1.0 op_sel_hi:[1,0]
	v_pk_add_f32 v[134:135], v[134:135], 1.0 op_sel_hi:[1,0]
	v_pk_add_f32 v[136:137], v[136:137], 1.0 op_sel_hi:[1,0]
	v_pk_add_f32 v[138:139], v[138:139], 1.0 op_sel_hi:[1,0]
	v_rcp_f32_e32 v132, v132
	v_rcp_f32_e32 v133, v133
	v_rcp_f32_e32 v134, v134
	v_rcp_f32_e32 v135, v135
	v_rcp_f32_e32 v136, v136
	v_rcp_f32_e32 v137, v137
	v_rcp_f32_e32 v138, v138
	v_rcp_f32_e32 v139, v139
	v_pk_mul_f32 v[132:133], v[58:59], v[132:133]
	v_pk_mul_f32 v[134:135], v[60:61], v[134:135]
	v_pk_mul_f32 v[136:137], v[50:51], v[136:137]
	v_pk_mul_f32 v[138:139], v[52:53], v[138:139]
	v_cvt_pk_bf16_f32 v144, v132, v133
	v_cvt_pk_bf16_f32 v145, v134, v135
	v_cvt_pk_bf16_f32 v146, v136, v137
	v_cvt_pk_bf16_f32 v147, v138, v139
	s_nop 1
	v_permlane16_swap_b32_e32 v144, v146
	v_permlane16_swap_b32_e32 v145, v147
	s_nop 1
	global_store_dwordx4 v173, v[144:147], s[4:5] offset:128
	s_add_u32 s4, s14, 163840
	s_addc_u32 s5, s15, 0
	v_pk_mul_f32 v[132:133], v[46:47], v[130:131]
	v_pk_mul_f32 v[134:135], v[48:49], v[130:131]
	v_pk_mul_f32 v[136:137], v[38:39], v[130:131]
	v_pk_mul_f32 v[138:139], v[40:41], v[130:131]
	v_exp_f32_e32 v132, v132
	v_exp_f32_e32 v133, v133
	v_exp_f32_e32 v134, v134
	v_exp_f32_e32 v135, v135
	v_exp_f32_e32 v136, v136
	v_exp_f32_e32 v137, v137
	v_exp_f32_e32 v138, v138
	v_exp_f32_e32 v139, v139
	v_pk_add_f32 v[132:133], v[132:133], 1.0 op_sel_hi:[1,0]
	v_pk_add_f32 v[134:135], v[134:135], 1.0 op_sel_hi:[1,0]
	v_pk_add_f32 v[136:137], v[136:137], 1.0 op_sel_hi:[1,0]
	v_pk_add_f32 v[138:139], v[138:139], 1.0 op_sel_hi:[1,0]
	v_rcp_f32_e32 v132, v132
	v_rcp_f32_e32 v133, v133
	v_rcp_f32_e32 v134, v134
	v_rcp_f32_e32 v135, v135
	v_rcp_f32_e32 v136, v136
	v_rcp_f32_e32 v137, v137
	v_rcp_f32_e32 v138, v138
	v_rcp_f32_e32 v139, v139
	v_pk_mul_f32 v[132:133], v[22:23], v[132:133]
	v_pk_mul_f32 v[134:135], v[24:25], v[134:135]
	v_pk_mul_f32 v[136:137], v[18:19], v[136:137]
	v_pk_mul_f32 v[138:139], v[20:21], v[138:139]
	v_cvt_pk_bf16_f32 v140, v132, v133
	v_cvt_pk_bf16_f32 v141, v134, v135
	v_cvt_pk_bf16_f32 v142, v136, v137
	v_cvt_pk_bf16_f32 v143, v138, v139
	s_nop 1
	v_permlane16_swap_b32_e32 v140, v142
	v_permlane16_swap_b32_e32 v141, v143
	s_nop 1
	global_store_dwordx4 v173, v[140:143], s[4:5] offset:0
	v_pk_mul_f32 v[132:133], v[6:7], v[130:131]
	v_pk_mul_f32 v[134:135], v[8:9], v[130:131]
	v_pk_mul_f32 v[136:137], v[2:3], v[130:131]
	v_pk_mul_f32 v[138:139], v[4:5], v[130:131]
	v_exp_f32_e32 v132, v132
	v_exp_f32_e32 v133, v133
	v_exp_f32_e32 v134, v134
	v_exp_f32_e32 v135, v135
	v_exp_f32_e32 v136, v136
	v_exp_f32_e32 v137, v137
	v_exp_f32_e32 v138, v138
	v_exp_f32_e32 v139, v139
	v_pk_add_f32 v[132:133], v[132:133], 1.0 op_sel_hi:[1,0]
	v_pk_add_f32 v[134:135], v[134:135], 1.0 op_sel_hi:[1,0]
	v_pk_add_f32 v[136:137], v[136:137], 1.0 op_sel_hi:[1,0]
	v_pk_add_f32 v[138:139], v[138:139], 1.0 op_sel_hi:[1,0]
	v_rcp_f32_e32 v132, v132
	v_rcp_f32_e32 v133, v133
	v_rcp_f32_e32 v134, v134
	v_rcp_f32_e32 v135, v135
	v_rcp_f32_e32 v136, v136
	v_rcp_f32_e32 v137, v137
	v_rcp_f32_e32 v138, v138
	v_rcp_f32_e32 v139, v139
	v_pk_mul_f32 v[132:133], v[42:43], v[132:133]
	v_pk_mul_f32 v[134:135], v[44:45], v[134:135]
	v_pk_mul_f32 v[136:137], v[34:35], v[136:137]
	v_pk_mul_f32 v[138:139], v[36:37], v[138:139]
	v_cvt_pk_bf16_f32 v144, v132, v133
	v_cvt_pk_bf16_f32 v145, v134, v135
	v_cvt_pk_bf16_f32 v146, v136, v137
	v_cvt_pk_bf16_f32 v147, v138, v139
	s_nop 1
	v_permlane16_swap_b32_e32 v144, v146
	v_permlane16_swap_b32_e32 v145, v147
	s_nop 1
	global_store_dwordx4 v173, v[144:147], s[4:5] offset:128
	s_branch .LBB0_187
